# P3 attention tile loop by hand: K-fragment reads all in flight with counted lgkmcnt, neighbourhood mask precomputed once and fed as MFMA C operand, bias reads via one address + early issue, row max vi
# speedup vs baseline: 1.0130x; 1.0130x over previous
.LBB0_527:
	global_load_dword v6, v[4:5], off
	v_add_u32_e32 v3, 0x200, v3
	v_cmp_lt_u32_e32 vcc, s8, v3
	v_lshl_add_u64 v[4:5], v[4:5], 0, s[2:3]
	s_or_b64 s[0:1], vcc, s[0:1]
	s_waitcnt vmcnt(0)
	v_mul_f32_e32 v6, 0x3fb8aa3b, v6
	ds_write_b32 v1, v6
	v_add_u32_e32 v1, 0x800, v1
	s_andn2_b64 exec, exec, s[0:1]
	s_cbranch_execnz .LBB0_527
	s_or_b64 exec, exec, s[0:1]
	s_cmpk_gt_i32 s14, 0x1ff
	s_waitcnt lgkmcnt(0)
	s_barrier
	s_cbranch_scc1 .LBB0_550
	v_and_b32_e32 v1, 31, v0
	s_lshl_b32 s0, s92, 5
	v_lshrrev_b32_e32 v5, 4, v178
	v_and_or_b32 v146, s0, 32, v1
	v_lshlrev_b32_e32 v1, 2, v5
	s_bfe_u32 s0, s95, 0x20006
	v_and_b32_e32 v7, 15, v0
	v_lshrrev_b32_e32 v8, 1, v178
	v_bitop3_b32 v7, s0, v7, v1 bitop3:0x36
	v_lshlrev_b32_e32 v1, 1, v0
	v_and_b32_e32 v8, 4, v8
	v_and_or_b32 v1, v1, 8, v8
	v_lshrrev_b32_e32 v4, 5, v178
	v_and_or_b32 v8, v0, 19, v1
	v_and_b32_e32 v2, 12, v2
	v_lshrrev_b32_e32 v9, 2, v1
	v_lshlrev_b32_e32 v1, 8, v8
	v_bitop3_b32 v8, v9, v4, v2 bitop3:0x36
	v_lshlrev_b32_e32 v147, 4, v8
	v_or_b32_e32 v8, 2, v4
	v_bitop3_b32 v8, v9, v8, v2 bitop3:0x36
	v_lshlrev_b32_e32 v156, 4, v8
	v_or_b32_e32 v8, 4, v4
	v_bitop3_b32 v8, v9, v8, v2 bitop3:0x36
	v_lshlrev_b32_e32 v157, 4, v8
	v_or_b32_e32 v8, 6, v4
	v_bitop3_b32 v8, v9, v8, v2 bitop3:0x36
	v_lshlrev_b32_e32 v158, 4, v8
	v_or_b32_e32 v8, 8, v4
	v_bitop3_b32 v8, v9, v8, v2 bitop3:0x36
	v_lshlrev_b32_e32 v159, 4, v8
	v_or_b32_e32 v8, 10, v4
	v_bitop3_b32 v8, v9, v8, v2 bitop3:0x36
	v_lshlrev_b32_e32 v160, 4, v8
	v_or_b32_e32 v8, 12, v4
	v_bitop3_b32 v8, v9, v8, v2 bitop3:0x36
	v_lshlrev_b32_e32 v161, 4, v8
	v_or_b32_e32 v8, 14, v4
	v_bitop3_b32 v2, v9, v8, v2 bitop3:0x36
	v_lshlrev_b32_e32 v162, 4, v2
	v_lshlrev_b32_e32 v2, 12, v5
	v_lshl_or_b32 v2, s92, 14, v2
	v_lshl_or_b32 v148, v7, 4, v2
	v_lshrrev_b32_e32 v7, 3, v178
	v_bfe_u32 v8, v178, 1, 1
	v_and_or_b32 v7, v7, 2, v8
	v_lshlrev_b32_e32 v8, 3, v0
	v_mov_b32_e32 v9, 0x2000
	v_lshlrev_b32_e32 v6, 3, v4
	v_bfe_u32 v2, v0, 2, 2
	v_and_b32_e32 v5, 12, v0
	v_and_or_b32 v8, v8, 8, v9
	v_lshlrev_b32_e32 v9, 1, v4
	v_or_b32_e32 v2, v2, v6
	v_or_b32_e32 v10, v9, v5
	v_lshl_or_b32 v11, v2, 8, v8
	v_bitop3_b32 v12, v7, v10, 4 bitop3:0x36
	v_bitop3_b32 v13, v7, v10, 8 bitop3:0x36
	v_bitop3_b32 v10, v7, v10, 12 bitop3:0x36
	v_or_b32_e32 v2, 4, v2
	v_bitop3_b32 v9, v9, v7, v5 bitop3:0x36
	v_lshl_or_b32 v166, v10, 4, v11
	v_lshrrev_b32_e32 v10, 2, v2
	v_lshl_or_b32 v163, v9, 4, v11
	v_or_b32_e32 v9, 4, v7
	v_lshl_or_b32 v164, v12, 4, v11
	v_or_b32_e32 v12, 8, v7
	v_lshl_or_b32 v165, v13, 4, v11
	v_or_b32_e32 v13, 12, v7
	v_lshl_or_b32 v2, v2, 8, v8
	v_bitop3_b32 v7, v10, v7, v5 bitop3:0x36
	v_lshl_or_b32 v167, v7, 4, v2
	v_bitop3_b32 v7, v10, v9, v5 bitop3:0x36
	v_sub_u32_e64 v3, v146, 8 clamp
	v_lshl_or_b32 v168, v7, 4, v2
	v_bitop3_b32 v7, v10, v12, v5 bitop3:0x36
	v_bitop3_b32 v5, v10, v13, v5 bitop3:0x36
	v_lshl_or_b32 v169, v7, 4, v2
	v_lshl_or_b32 v170, v5, 4, v2
	v_min_u32_e32 v2, 48, v3
	s_lshl_b32 s0, s92, 10
	v_sub_u32_e32 v171, v6, v2
	v_sub_u32_e32 v2, v6, v146
	v_mov_b32_e32 v151, 0
	s_add_i32 s13, s0, 0
	v_lshl_add_u32 v172, v2, 2, 0
	v_mbcnt_lo_u32_b32 v2, -1, 0
	s_lshr_b32 s12, s95, 7
	v_mov_b32_e32 v149, v151
	s_mov_b32 s1, 0
	v_cmp_gt_u32_e64 s[2:3], 32, v178
	v_lshlrev_b32_e32 v152, 1, v6
	v_mov_b32_e32 v153, v151
	s_add_i32 s15, s13, 0x8000
	s_add_i32 s24, s13, 0xa000
	s_add_i32 s25, s13, 0xc000
	s_add_i32 s35, s13, 0xe000
	s_add_i32 s46, s13, 0x10000
	s_add_i32 s47, s13, 0x12000
	s_add_i32 s57, s13, 0x14000
	s_add_i32 s60, s13, 0x16000
	s_add_i32 s61, s13, 0x18000
	s_add_i32 s63, s13, 0x1a000
	s_movk_i32 s70, 0xffef
	v_lshlrev_b32_e32 v150, 3, v4
	v_mov_b32_e32 v173, 0xff800000
	v_mbcnt_hi_u32_b32 v174, -1, v2
	v_xor_b32_e32 v197, 32, v174
	v_lshlrev_b32_e32 v197, 2, v197
	v_add_u32_e32 v198, 0, v171
	v_cmp_gt_u32_e32 vcc, 16, v198
	s_nop 1
	v_cndmask_b32_e32 v222, v173, v151, vcc
	v_add_u32_e32 v198, 1, v171
	v_cmp_gt_u32_e32 vcc, 16, v198
	s_nop 1
	v_cndmask_b32_e32 v223, v173, v151, vcc
	v_add_u32_e32 v198, 2, v171
	v_cmp_gt_u32_e32 vcc, 16, v198
	s_nop 1
	v_cndmask_b32_e32 v224, v173, v151, vcc
	v_add_u32_e32 v198, 3, v171
	v_cmp_gt_u32_e32 vcc, 16, v198
	s_nop 1
	v_cndmask_b32_e32 v225, v173, v151, vcc
	v_add_u32_e32 v198, 4, v171
	v_cmp_gt_u32_e32 vcc, 16, v198
	s_nop 1
	v_cndmask_b32_e32 v226, v173, v151, vcc
	v_add_u32_e32 v198, 5, v171
	v_cmp_gt_u32_e32 vcc, 16, v198
	s_nop 1
	v_cndmask_b32_e32 v227, v173, v151, vcc
	v_add_u32_e32 v198, 6, v171
	v_cmp_gt_u32_e32 vcc, 16, v198
	s_nop 1
	v_cndmask_b32_e32 v228, v173, v151, vcc
	v_add_u32_e32 v198, 7, v171
	v_cmp_gt_u32_e32 vcc, 16, v198
	s_nop 1
	v_cndmask_b32_e32 v229, v173, v151, vcc
	v_add_u32_e32 v198, 16, v171
	v_cmp_gt_u32_e32 vcc, 16, v198
	s_nop 1
	v_cndmask_b32_e32 v230, v173, v151, vcc
	v_add_u32_e32 v198, 17, v171
	v_cmp_gt_u32_e32 vcc, 16, v198
	s_nop 1
	v_cndmask_b32_e32 v231, v173, v151, vcc
	v_add_u32_e32 v198, 18, v171
	v_cmp_gt_u32_e32 vcc, 16, v198
	s_nop 1
	v_cndmask_b32_e32 v232, v173, v151, vcc
	v_add_u32_e32 v198, 19, v171
	v_cmp_gt_u32_e32 vcc, 16, v198
	s_nop 1
	v_cndmask_b32_e32 v233, v173, v151, vcc
	v_add_u32_e32 v198, 20, v171
	v_cmp_gt_u32_e32 vcc, 16, v198
	s_nop 1
	v_cndmask_b32_e32 v234, v173, v151, vcc
	v_add_u32_e32 v198, 21, v171
	v_cmp_gt_u32_e32 vcc, 16, v198
	s_nop 1
	v_cndmask_b32_e32 v235, v173, v151, vcc
	v_add_u32_e32 v198, 22, v171
	v_cmp_gt_u32_e32 vcc, 16, v198
	s_nop 1
	v_cndmask_b32_e32 v236, v173, v151, vcc
	v_add_u32_e32 v198, 23, v171
	v_cmp_gt_u32_e32 vcc, 16, v198
	s_nop 1
	v_cndmask_b32_e32 v237, v173, v151, vcc
	v_add_u32_e32 v198, 32, v171
	v_cmp_gt_u32_e32 vcc, 16, v198
	s_nop 1
	v_cndmask_b32_e32 v238, v173, v151, vcc
	v_add_u32_e32 v198, 33, v171
	v_cmp_gt_u32_e32 vcc, 16, v198
	s_nop 1
	v_cndmask_b32_e32 v239, v173, v151, vcc
	v_add_u32_e32 v198, 34, v171
	v_cmp_gt_u32_e32 vcc, 16, v198
	s_nop 1
	v_cndmask_b32_e32 v240, v173, v151, vcc
	v_add_u32_e32 v198, 35, v171
	v_cmp_gt_u32_e32 vcc, 16, v198
	s_nop 1
	v_cndmask_b32_e32 v241, v173, v151, vcc
	v_add_u32_e32 v198, 36, v171
	v_cmp_gt_u32_e32 vcc, 16, v198
	s_nop 1
	v_cndmask_b32_e32 v242, v173, v151, vcc
	v_add_u32_e32 v198, 37, v171
	v_cmp_gt_u32_e32 vcc, 16, v198
	s_nop 1
	v_cndmask_b32_e32 v243, v173, v151, vcc
	v_add_u32_e32 v198, 38, v171
	v_cmp_gt_u32_e32 vcc, 16, v198
	s_nop 1
	v_cndmask_b32_e32 v244, v173, v151, vcc
	v_add_u32_e32 v198, 39, v171
	v_cmp_gt_u32_e32 vcc, 16, v198
	s_nop 1
	v_cndmask_b32_e32 v245, v173, v151, vcc
	v_add_u32_e32 v198, 48, v171
	v_cmp_gt_u32_e32 vcc, 16, v198
	s_nop 1
	v_cndmask_b32_e32 v246, v173, v151, vcc
	v_add_u32_e32 v198, 49, v171
	v_cmp_gt_u32_e32 vcc, 16, v198
	s_nop 1
	v_cndmask_b32_e32 v247, v173, v151, vcc
	v_add_u32_e32 v198, 50, v171
	v_cmp_gt_u32_e32 vcc, 16, v198
	s_nop 1
	v_cndmask_b32_e32 v248, v173, v151, vcc
	v_add_u32_e32 v198, 51, v171
	v_cmp_gt_u32_e32 vcc, 16, v198
	s_nop 1
	v_cndmask_b32_e32 v249, v173, v151, vcc
	v_add_u32_e32 v198, 52, v171
	v_cmp_gt_u32_e32 vcc, 16, v198
	s_nop 1
	v_cndmask_b32_e32 v250, v173, v151, vcc
	v_add_u32_e32 v198, 53, v171
	v_cmp_gt_u32_e32 vcc, 16, v198
	s_nop 1
	v_cndmask_b32_e32 v251, v173, v151, vcc
	v_add_u32_e32 v198, 54, v171
	v_cmp_gt_u32_e32 vcc, 16, v198
	s_nop 1
	v_cndmask_b32_e32 v252, v173, v151, vcc
	v_add_u32_e32 v198, 55, v171
	v_cmp_gt_u32_e32 vcc, 16, v198
	s_nop 1
	v_cndmask_b32_e32 v253, v173, v151, vcc
	s_branch .LBB0_531

.LBB0_539:
	s_andn2_b64 vcc, exec, s[42:43]
	s_cbranch_vccnz .LBB0_545
	s_lshl_b32 s18, s77, 14
	s_add_i32 s18, s18, 0
	s_add_i32 s19, s18, 0x8000
	v_add3_u32 v198, s18, v147, v1
	ds_read_b128 v[198:201], v198 offset:32768
	v_add3_u32 v202, s18, v156, v1
	ds_read_b128 v[202:205], v202 offset:32768
	v_add3_u32 v206, s18, v157, v1
	ds_read_b128 v[206:209], v206 offset:32768
	v_add3_u32 v210, s18, v158, v1
	ds_read_b128 v[210:213], v210 offset:32768
	v_add3_u32 v214, s18, v159, v1
	ds_read_b128 v[214:217], v214 offset:32768
	v_add3_u32 v218, s18, v160, v1
	ds_read_b128 v[218:221], v218 offset:32768
	v_add_u32_e32 v180, s19, v163
	v_add_u32_e32 v181, s19, v164
	v_add_u32_e32 v182, s19, v165
	v_add_u32_e32 v183, s19, v166
	v_add_u32_e32 v184, s19, v167
	v_add_u32_e32 v185, s19, v168
	v_add_u32_e32 v186, s19, v169
	v_add_u32_e32 v187, s19, v170
	v_add3_u32 v188, s18, v161, v1
	v_add3_u32 v189, s18, v162, v1
	ds_read_b64_tr_b16 v[142:143], v180
	ds_read_b64_tr_b16 v[126:127], v180 offset:4096
	ds_read_b64_tr_b16 v[138:139], v181
	ds_read_b64_tr_b16 v[122:123], v181 offset:4096
	s_andn2_b64 vcc, exec, s[40:41]
	s_waitcnt lgkmcnt(9)
	s_cbranch_vccnz .Lp3_m0ctx
	s_bitcmp1_b32 s75, 5
	s_cbranch_scc1 .Lp3_m0k1
	v_mfma_f32_32x32x16_bf16 v[66:81], v[198:201], v[82:85], v[222:237]
	s_branch .Lp3_m0join
.Lp3_m0k1:
	v_mfma_f32_32x32x16_bf16 v[66:81], v[198:201], v[82:85], v[238:253]
	s_branch .Lp3_m0join
.Lp3_m0ctx:
	v_mfma_f32_32x32x16_bf16 v[66:81], v[198:201], v[82:85], 0
.Lp3_m0join:
	ds_read_b128 v[198:201], v188 offset:32768
	ds_read_b64_tr_b16 v[134:135], v182
	ds_read_b64_tr_b16 v[118:119], v182 offset:4096
	s_waitcnt lgkmcnt(11)
	v_mfma_f32_32x32x16_bf16 v[66:81], v[202:205], v[86:89], v[66:81]
	ds_read_b128 v[202:205], v189 offset:32768
	ds_read_b64_tr_b16 v[130:131], v183
	ds_read_b64_tr_b16 v[114:115], v183 offset:4096
	s_waitcnt lgkmcnt(13)
	v_mfma_f32_32x32x16_bf16 v[66:81], v[206:209], v[90:93], v[66:81]
	ds_read_b64_tr_b16 v[144:145], v184
	ds_read_b64_tr_b16 v[128:129], v184 offset:4096
	s_waitcnt lgkmcnt(13)
	v_mfma_f32_32x32x16_bf16 v[66:81], v[210:213], v[94:97], v[66:81]
	ds_read_b64_tr_b16 v[140:141], v185
	ds_read_b64_tr_b16 v[124:125], v185 offset:4096
	s_waitcnt lgkmcnt(13)
	v_mfma_f32_32x32x16_bf16 v[66:81], v[214:217], v[98:101], v[66:81]
	ds_read_b64_tr_b16 v[136:137], v186
	ds_read_b64_tr_b16 v[120:121], v186 offset:4096
	s_waitcnt lgkmcnt(13)
	v_mfma_f32_32x32x16_bf16 v[66:81], v[218:221], v[102:105], v[66:81]
	ds_read_b64_tr_b16 v[132:133], v187
	ds_read_b64_tr_b16 v[116:117], v187 offset:4096
	s_cbranch_vccnz .Lp3_ctx67
	s_sub_i32 s18, s79, s0
	s_and_b32 s19, s75, 32
	s_mulk_i32 s18, 0x7c
	s_lshl_b32 s33, s19, 2
	s_add_i32 s33, s33, s18
	s_addk_i32 s33, 0x7a0
	v_add_u32_e32 v188, s33, v176
	s_waitcnt lgkmcnt(7)
	ds_read2_b32 v[180:181], v188 offset1:1
	ds_read2_b32 v[182:183], v188 offset0:2 offset1:3
	ds_read2_b32 v[184:185], v188 offset0:4 offset1:5
	ds_read2_b32 v[186:187], v188 offset0:6 offset1:7
	ds_read2_b32 v[190:191], v188 offset0:16 offset1:17
	ds_read2_b32 v[192:193], v188 offset0:18 offset1:19
	ds_read2_b32 v[194:195], v188 offset0:20 offset1:21
	ds_read2_b32 v[188:189], v188 offset0:22 offset1:23
	v_mfma_f32_32x32x16_bf16 v[66:81], v[198:201], v[106:109], v[66:81]
	v_mfma_f32_32x32x16_bf16 v[66:81], v[202:205], v[110:113], v[66:81]
	s_waitcnt lgkmcnt(0)
	s_nop 10
	v_pk_add_f32 v[66:67], v[66:67], v[180:181]
	v_pk_add_f32 v[68:69], v[68:69], v[182:183]
	v_pk_add_f32 v[70:71], v[70:71], v[184:185]
	v_pk_add_f32 v[72:73], v[72:73], v[186:187]
	v_pk_add_f32 v[74:75], v[74:75], v[190:191]
	v_pk_add_f32 v[76:77], v[76:77], v[192:193]
	v_pk_add_f32 v[78:79], v[78:79], v[194:195]
	v_pk_add_f32 v[80:81], v[80:81], v[188:189]
	s_branch .Lp3_sm
.Lp3_ctx67:
	s_waitcnt lgkmcnt(13)
	v_mfma_f32_32x32x16_bf16 v[66:81], v[198:201], v[106:109], v[66:81]
	s_waitcnt lgkmcnt(10)
	v_mfma_f32_32x32x16_bf16 v[66:81], v[202:205], v[110:113], v[66:81]

.Lp3_sm:
	v_max_f32_e32 v179, v66, v67
	v_max3_f32 v179, v179, v68, v69
	v_max3_f32 v179, v179, v70, v71
	v_max3_f32 v179, v179, v72, v73
	v_max3_f32 v179, v179, v74, v75
	v_max3_f32 v179, v179, v76, v77
	v_max3_f32 v179, v179, v78, v79
	v_max3_f32 v179, v179, v80, v81
	v_mov_b32_e32 v180, v179
	s_nop 1
	v_permlane32_swap_b32_e32 v180, v179
	v_max_f32_e32 v179, v179, v180
	v_cmp_gt_f32_e32 vcc, v179, v177
	s_cbranch_vccz .LBB0_544
	v_max_f32_e32 v179, v179, v179
	v_max_f32_e32 v180, v177, v177
	v_max_f32_e32 v179, v180, v179
	v_sub_f32_e32 v177, v177, v179
	v_exp_f32_e32 v180, v177
	v_mov_b32_e32 v177, v179
	v_pk_mul_f32 v[64:65], v[64:65], v[180:181] op_sel_hi:[1,0]
	v_pk_mul_f32 v[62:63], v[62:63], v[180:181] op_sel_hi:[1,0]
	v_pk_mul_f32 v[60:61], v[60:61], v[180:181] op_sel_hi:[1,0]
	v_pk_mul_f32 v[58:59], v[58:59], v[180:181] op_sel_hi:[1,0]
	v_pk_mul_f32 v[56:57], v[56:57], v[180:181] op_sel_hi:[1,0]
	v_pk_mul_f32 v[54:55], v[54:55], v[180:181] op_sel_hi:[1,0]
	v_pk_mul_f32 v[52:53], v[52:53], v[180:181] op_sel_hi:[1,0]
	v_pk_mul_f32 v[50:51], v[50:51], v[180:181] op_sel_hi:[1,0]
	v_pk_mul_f32 v[48:49], v[48:49], v[180:181] op_sel_hi:[1,0]
	v_pk_mul_f32 v[46:47], v[46:47], v[180:181] op_sel_hi:[1,0]
	v_pk_mul_f32 v[44:45], v[44:45], v[180:181] op_sel_hi:[1,0]
	v_pk_mul_f32 v[42:43], v[42:43], v[180:181] op_sel_hi:[1,0]
	v_pk_mul_f32 v[40:41], v[40:41], v[180:181] op_sel_hi:[1,0]
	v_pk_mul_f32 v[38:39], v[38:39], v[180:181] op_sel_hi:[1,0]
	v_pk_mul_f32 v[36:37], v[36:37], v[180:181] op_sel_hi:[1,0]
	v_pk_mul_f32 v[34:35], v[34:35], v[180:181] op_sel_hi:[1,0]
	v_pk_mul_f32 v[32:33], v[32:33], v[180:181] op_sel_hi:[1,0]
	v_pk_mul_f32 v[30:31], v[30:31], v[180:181] op_sel_hi:[1,0]
	v_pk_mul_f32 v[28:29], v[28:29], v[180:181] op_sel_hi:[1,0]
	v_pk_mul_f32 v[26:27], v[26:27], v[180:181] op_sel_hi:[1,0]
	v_pk_mul_f32 v[24:25], v[24:25], v[180:181] op_sel_hi:[1,0]
	v_pk_mul_f32 v[22:23], v[22:23], v[180:181] op_sel_hi:[1,0]
	v_pk_mul_f32 v[20:21], v[20:21], v[180:181] op_sel_hi:[1,0]
	v_pk_mul_f32 v[18:19], v[18:19], v[180:181] op_sel_hi:[1,0]
	v_pk_mul_f32 v[16:17], v[16:17], v[180:181] op_sel_hi:[1,0]
	v_pk_mul_f32 v[14:15], v[14:15], v[180:181] op_sel_hi:[1,0]
	v_pk_mul_f32 v[12:13], v[12:13], v[180:181] op_sel_hi:[1,0]
	v_pk_mul_f32 v[10:11], v[10:11], v[180:181] op_sel_hi:[1,0]
	v_pk_mul_f32 v[8:9], v[8:9], v[180:181] op_sel_hi:[1,0]
	v_pk_mul_f32 v[6:7], v[6:7], v[180:181] op_sel_hi:[1,0]
	v_pk_mul_f32 v[4:5], v[4:5], v[180:181] op_sel_hi:[1,0]
	v_pk_mul_f32 v[2:3], v[2:3], v[180:181] op_sel_hi:[1,0]
	v_mul_f32_e32 v175, v175, v180
.LBB0_544:
	v_sub_f32_e32 v66, v66, v177
	v_exp_f32_e32 v179, v66
	v_sub_f32_e32 v66, v67, v177
	v_exp_f32_e32 v180, v66
	v_sub_f32_e32 v66, v68, v177
	v_exp_f32_e32 v181, v66
	v_sub_f32_e32 v66, v69, v177
	v_exp_f32_e32 v182, v66
	v_sub_f32_e32 v66, v70, v177
	v_exp_f32_e32 v70, v66
	v_sub_f32_e32 v66, v71, v177
	v_exp_f32_e32 v71, v66
	v_sub_f32_e32 v66, v72, v177
	v_exp_f32_e32 v72, v66
	v_sub_f32_e32 v66, v73, v177
	v_exp_f32_e32 v73, v66
	v_cvt_pk_bf16_f32 v66, v179, v180
	v_cvt_pk_bf16_f32 v67, v181, v182
	v_cvt_pk_bf16_f32 v68, v70, v71
	v_cvt_pk_bf16_f32 v69, v72, v73
	s_waitcnt lgkmcnt(0)
	v_sub_f32_e32 v74, v74, v177
	v_sub_f32_e32 v75, v75, v177
	v_mfma_f32_32x32x16_bf16 v[50:65], v[142:145], v[66:69], v[50:65]
	v_sub_f32_e32 v76, v76, v177
	v_sub_f32_e32 v77, v77, v177
	v_sub_f32_e32 v78, v78, v177
	v_sub_f32_e32 v79, v79, v177
	v_sub_f32_e32 v80, v80, v177
	v_exp_f32_e32 v74, v74
	v_exp_f32_e32 v75, v75
	v_mfma_f32_32x32x16_bf16 v[34:49], v[138:141], v[66:69], v[34:49]
	v_exp_f32_e32 v76, v76
	v_exp_f32_e32 v77, v77
	v_exp_f32_e32 v78, v78
	v_exp_f32_e32 v79, v79
	v_exp_f32_e32 v80, v80
	v_mfma_f32_32x32x16_bf16 v[18:33], v[134:137], v[66:69], v[18:33]
	v_mfma_f32_32x32x16_bf16 v[2:17], v[130:133], v[66:69], v[2:17]
	v_sub_f32_e32 v66, v81, v177
	v_exp_f32_e32 v81, v66
	v_cvt_pk_bf16_f32 v66, v74, v75
	v_cvt_pk_bf16_f32 v67, v76, v77
	v_cvt_pk_bf16_f32 v68, v78, v79
	v_cvt_pk_bf16_f32 v69, v80, v81
	s_nop 1
	v_mfma_f32_32x32x16_bf16 v[50:65], v[126:129], v[66:69], v[50:65]
	v_add_f32_e32 v126, v180, v179
	v_add_f32_e32 v126, v181, v126
	v_mfma_f32_32x32x16_bf16 v[34:49], v[122:125], v[66:69], v[34:49]
	v_add_f32_e32 v122, v182, v126
	v_add_f32_e32 v70, v70, v122
	v_add_f32_e32 v70, v71, v70
	v_add_f32_e32 v70, v72, v70
	v_add_f32_e32 v70, v73, v70
	v_add_f32_e32 v70, v74, v70
	v_add_f32_e32 v70, v75, v70
	v_mfma_f32_32x32x16_bf16 v[18:33], v[118:121], v[66:69], v[18:33]
	v_add_f32_e32 v70, v76, v70
	v_add_f32_e32 v70, v77, v70
	v_add_f32_e32 v70, v78, v70
	v_add_f32_e32 v70, v79, v70
	v_add_f32_e32 v70, v80, v70
	v_add_f32_e32 v70, v81, v70
	v_add_f32_e32 v175, v175, v70
	v_mfma_f32_32x32x16_bf16 v[2:17], v[114:117], v[66:69], v[2:17]
